# v39 + LN2 row-loop wait ladder counts the 8 hb/hlo stores issued after the prefetched loads (strict waits only in the final-LN mode)
# baseline (speedup 1.0000x reference)
.Lln2_nostage:
	v_and_b32_e32 v2, 63, v0
	s_nop 0
	global_load_ushort v1, v173, s[4:5]
	s_waitcnt lgkmcnt(0)
	s_add_u32 s6, s12, 0x8000
	s_addc_u32 s7, s13, 0
	s_add_u32 s20, s14, 0x4e09000
	s_addc_u32 s21, s15, 0
	s_add_u32 s0, s14, 0x11139000
	s_addc_u32 s4, s15, 0
	s_add_u32 s22, s14, 0x151f9000
	s_addc_u32 s23, s15, 0
	s_add_u32 s24, s14, 0xf0b1000
	v_ashrrev_i32_e32 v0, 6, v0
	s_addc_u32 s25, s15, 0
	v_mul_lo_u32 v3, v0, s42
	s_cmp_lg_u32 s16, 3
	v_add_u32_e32 v0, s2, v3
	s_cselect_b64 s[26:27], -1, 0
	s_and_b32 s100, s26, 1
	s_cmp_eq_u32 s16, 3
	v_cmp_gt_i32_e32 vcc, s58, v0
	s_cselect_b32 s29, s4, s7
	s_cselect_b32 s28, s0, s6
	s_waitcnt vmcnt(0)
	v_readfirstlane_b32 s0, v1
	v_ashrrev_i32_e32 v1, 31, v0
	s_and_saveexec_b64 s[16:17], vcc
	s_cbranch_execz .LBB0_1108
	v_lshlrev_b64 v[26:27], 11, v[0:1]
	v_lshl_or_b32 v26, v2, 3, v26
	s_mov_b32 s18, 0xfe000000
	v_lshl_add_u64 v[6:7], s[22:23], 0, v[26:27]
	s_mov_b32 s19, -1
	v_lshl_add_u64 v[4:5], s[24:25], 0, v[26:27]
	v_lshl_add_u64 v[6:7], v[6:7], 0, s[18:19]
	v_cmp_gt_i32_e64 s[4:5], s73, v0
	v_lshl_add_u64 v[14:15], s[28:29], 0, v[26:27]
	v_lshl_add_u64 v[18:19], s[20:21], 0, v[26:27]
	v_cndmask_b32_e64 v5, v7, v5, s[4:5]
	v_cndmask_b32_e64 v4, v6, v4, s[4:5]
	v_or_b32_e32 v6, 0x200, v26
	v_mov_b32_e32 v7, v27
	v_lshl_add_u64 v[20:21], s[20:21], 0, v[6:7]
	v_lshl_add_u64 v[8:9], s[24:25], 0, v[6:7]
	v_lshl_add_u64 v[6:7], s[22:23], 0, v[6:7]
	v_lshl_add_u64 v[6:7], v[6:7], 0, s[18:19]
	v_cndmask_b32_e64 v7, v7, v9, s[4:5]
	v_cndmask_b32_e64 v6, v6, v8, s[4:5]
	v_or_b32_e32 v8, 0x400, v26
	v_mov_b32_e32 v9, v27
	v_lshl_add_u64 v[22:23], s[20:21], 0, v[8:9]
	v_lshl_add_u64 v[10:11], s[24:25], 0, v[8:9]
	v_lshl_add_u64 v[8:9], s[22:23], 0, v[8:9]
	v_lshl_add_u64 v[8:9], v[8:9], 0, s[18:19]
	v_cndmask_b32_e64 v9, v9, v11, s[4:5]
	v_cndmask_b32_e64 v8, v8, v10, s[4:5]
	v_or_b32_e32 v26, 0x600, v26
	global_load_dwordx2 v[4:5], v[4:5], off
	v_lshl_add_u64 v[24:25], s[20:21], 0, v[26:27]
	global_load_dwordx2 v[6:7], v[6:7], off
	s_nop 0
	global_load_dwordx2 v[16:17], v[8:9], off
	s_nop 0
	global_load_dwordx2 v[8:9], v[14:15], off
	global_load_dwordx2 v[10:11], v[14:15], off offset:512
	global_load_dwordx2 v[12:13], v[14:15], off offset:1024
	s_nop 0
	global_load_dwordx2 v[14:15], v[14:15], off offset:1536
	v_lshl_add_u64 v[28:29], s[24:25], 0, v[26:27]
	v_lshl_add_u64 v[26:27], s[22:23], 0, v[26:27]
	global_load_dwordx2 v[18:19], v[18:19], off
	s_nop 0
	global_load_dwordx2 v[20:21], v[20:21], off
	s_nop 0
	global_load_dwordx2 v[22:23], v[22:23], off
	s_nop 0
	global_load_dwordx2 v[24:25], v[24:25], off
	v_lshl_add_u64 v[26:27], v[26:27], 0, s[18:19]
	v_cndmask_b32_e64 v27, v27, v29, s[4:5]
	v_cndmask_b32_e64 v26, v26, v28, s[4:5]
	global_load_dwordx2 v[26:27], v[26:27], off

.LBB0_1112:
	s_waitcnt vmcnt(16)
	s_cmp_lg_u32 s100, 0
	s_cbranch_scc1 .Lln2w0
	s_waitcnt vmcnt(8)
.Lln2w0:
	v_lshlrev_b32_e32 v2, 16, v8
	v_and_b32_e32 v3, 0xffff0000, v8
	s_waitcnt vmcnt(12)
	s_cmp_lg_u32 s100, 0
	s_cbranch_scc1 .Lln2w1
	s_waitcnt vmcnt(4)
.Lln2w1:
	v_lshlrev_b32_e32 v62, 16, v18
	v_and_b32_e32 v63, 0xffff0000, v18
	v_lshlrev_b32_e32 v60, 16, v9
	v_and_b32_e32 v61, 0xffff0000, v9
	v_lshlrev_b32_e32 v64, 16, v19
	v_and_b32_e32 v65, 0xffff0000, v19
	v_pk_add_f32 v[2:3], v[2:3], v[62:63]
	v_lshlrev_b32_e32 v62, 16, v4
	v_and_b32_e32 v63, 0xffff0000, v4
	v_pk_add_f32 v[60:61], v[60:61], v[64:65]
	v_lshlrev_b32_e32 v64, 16, v5
	v_and_b32_e32 v65, 0xffff0000, v5
	v_pk_add_f32 v[62:63], v[62:63], 0 op_sel_hi:[1,0]
	v_pk_add_f32 v[64:65], v[64:65], 0 op_sel_hi:[1,0]
	v_pk_fma_f32 v[2:3], v[2:3], s[80:81], v[62:63] op_sel_hi:[1,0,1]
	v_pk_fma_f32 v[74:75], v[60:61], s[80:81], v[64:65] op_sel_hi:[1,0,1]
	v_pk_mul_f32 v[64:65], v[2:3], v[2:3]
	v_pk_mul_f32 v[62:63], v[74:75], v[74:75]
	v_fmac_f32_e32 v65, v2, v2
	v_add_f32_e32 v76, v62, v65
	v_lshlrev_b32_e32 v62, 16, v10
	v_and_b32_e32 v63, 0xffff0000, v10
	s_waitcnt vmcnt(11)
	s_cmp_lg_u32 s100, 0
	s_cbranch_scc1 .Lln2w2
	s_waitcnt vmcnt(3)
.Lln2w2:
	v_lshlrev_b32_e32 v66, 16, v20
	v_and_b32_e32 v67, 0xffff0000, v20
	v_pk_add_f32 v[62:63], v[62:63], v[66:67]
	v_lshlrev_b32_e32 v66, 16, v6
	v_and_b32_e32 v67, 0xffff0000, v6
	v_lshlrev_b32_e32 v64, 16, v11
	v_and_b32_e32 v65, 0xffff0000, v11
	v_lshlrev_b32_e32 v68, 16, v21
	v_and_b32_e32 v69, 0xffff0000, v21
	v_pk_add_f32 v[66:67], v[66:67], 0 op_sel_hi:[1,0]
	v_add_f32_e32 v1, v2, v3
	v_pk_add_f32 v[64:65], v[64:65], v[68:69]
	v_lshlrev_b32_e32 v68, 16, v7
	v_and_b32_e32 v69, 0xffff0000, v7
	v_pk_fma_f32 v[70:71], v[62:63], s[80:81], v[66:67] op_sel_hi:[1,0,1]
	v_add_f32_e32 v61, v74, v1
	v_pk_add_f32 v[68:69], v[68:69], 0 op_sel_hi:[1,0]
	v_mul_f32_e32 v60, v71, v71
	v_pk_fma_f32 v[72:73], v[64:65], s[80:81], v[68:69] op_sel_hi:[1,0,1]
	v_pk_fma_f32 v[62:63], v[70:71], v[70:71], v[60:61] op_sel_hi:[1,1,0]
	v_mul_f32_e32 v60, v73, v73
	v_pk_fma_f32 v[62:63], v[72:73], v[72:73], v[62:63]
	s_waitcnt vmcnt(10)
	s_cmp_lg_u32 s100, 0
	s_cbranch_scc1 .Lln2w3
	s_waitcnt vmcnt(2)
.Lln2w3:
	v_lshlrev_b32_e32 v66, 16, v22
	v_pk_add_f32 v[82:83], v[60:61], v[62:63] op_sel_hi:[0,1]
	v_lshlrev_b32_e32 v62, 16, v12
	v_and_b32_e32 v63, 0xffff0000, v12
	v_and_b32_e32 v67, 0xffff0000, v22
	v_pk_add_f32 v[62:63], v[62:63], v[66:67]
	v_lshlrev_b32_e32 v66, 16, v16
	v_and_b32_e32 v67, 0xffff0000, v16
	v_lshlrev_b32_e32 v64, 16, v13
	v_and_b32_e32 v65, 0xffff0000, v13
	v_lshlrev_b32_e32 v68, 16, v23
	v_and_b32_e32 v69, 0xffff0000, v23
	v_pk_add_f32 v[66:67], v[66:67], 0 op_sel_hi:[1,0]
	v_pk_add_f32 v[64:65], v[64:65], v[68:69]
	v_lshlrev_b32_e32 v68, 16, v17
	v_and_b32_e32 v69, 0xffff0000, v17
	v_pk_fma_f32 v[66:67], v[62:63], s[80:81], v[66:67] op_sel_hi:[1,0,1]
	v_pk_add_f32 v[68:69], v[68:69], 0 op_sel_hi:[1,0]
	v_mul_f32_e32 v60, v67, v67
	v_pk_fma_f32 v[68:69], v[64:65], s[80:81], v[68:69] op_sel_hi:[1,0,1]
	v_pk_fma_f32 v[62:63], v[66:67], v[66:67], v[60:61] op_sel_hi:[1,1,0]
	v_mul_f32_e32 v60, v69, v69
	v_pk_fma_f32 v[62:63], v[68:69], v[68:69], v[62:63]
	s_waitcnt vmcnt(9)
	s_cmp_lg_u32 s100, 0
	s_cbranch_scc1 .Lln2w4
	s_waitcnt vmcnt(1)
.Lln2w4:
	v_lshlrev_b32_e32 v94, 16, v24
	v_pk_add_f32 v[92:93], v[60:61], v[62:63] op_sel_hi:[0,1]
	v_lshlrev_b32_e32 v62, 16, v14
	v_and_b32_e32 v63, 0xffff0000, v14
	v_and_b32_e32 v95, 0xffff0000, v24
	v_lshlrev_b32_e32 v64, 16, v15
	v_and_b32_e32 v65, 0xffff0000, v15
	v_lshlrev_b32_e32 v96, 16, v25
	v_and_b32_e32 v97, 0xffff0000, v25
	v_pk_add_f32 v[62:63], v[62:63], v[94:95]
	s_waitcnt vmcnt(8)
	s_cmp_lg_u32 s100, 0
	s_cbranch_scc1 .Lln2w5
	s_waitcnt vmcnt(0)
.Lln2w5:
	v_lshlrev_b32_e32 v94, 16, v26
	v_and_b32_e32 v95, 0xffff0000, v26
	v_add_f32_e32 v1, v70, v71
	v_pk_add_f32 v[64:65], v[64:65], v[96:97]
	v_lshlrev_b32_e32 v96, 16, v27
	v_and_b32_e32 v97, 0xffff0000, v27
	v_pk_add_f32 v[94:95], v[94:95], 0 op_sel_hi:[1,0]
	v_add_f32_e32 v1, v72, v1
	v_pk_add_f32 v[96:97], v[96:97], 0 op_sel_hi:[1,0]
	v_pk_fma_f32 v[62:63], v[62:63], s[80:81], v[94:95] op_sel_hi:[1,0,1]
	v_mul_f32_e32 v78, v75, v75
	v_add_f32_e32 v81, v73, v1
	v_add_f32_e32 v1, v66, v67
	v_pk_fma_f32 v[64:65], v[64:65], s[80:81], v[96:97] op_sel_hi:[1,0,1]
	v_mul_f32_e32 v94, v62, v62
	v_mul_f32_e32 v60, v63, v63
	v_mov_b32_e32 v79, v62
	v_mov_b32_e32 v77, v63
	v_mov_b32_e32 v95, v75
	v_add_f32_e32 v1, v68, v1
	v_mul_f32_e32 v80, v64, v64
	v_pk_add_f32 v[76:77], v[78:79], v[76:77]
	v_mov_b32_e32 v83, v64
	v_pk_add_f32 v[60:61], v[94:95], v[60:61]
	v_add_f32_e32 v85, v69, v1
	v_mul_f32_e32 v84, v65, v65
	v_pk_add_f32 v[76:77], v[82:83], v[76:77]
	v_mov_b32_e32 v93, v65
	v_pk_add_f32 v[60:61], v[80:81], v[60:61]
	v_pk_add_f32 v[76:77], v[92:93], v[76:77]
	v_pk_add_f32 v[60:61], v[84:85], v[60:61]
	s_movk_i32 s0, 0x3fff
	v_pk_add_f32 v[76:77], v[76:77], v[60:61]
	v_cmp_lt_i32_e32 vcc, s0, v0
	s_and_saveexec_b64 s[6:7], vcc
	s_cbranch_execz .LBB0_1116
	v_mov_b32_e32 v53, v173
	v_lshlrev_b64 v[60:61], 11, v[52:53]
	v_lshl_add_u64 v[60:61], v[50:51], 0, v[60:61]
	s_mov_b64 s[8:9], 0
	s_mov_b64 s[8:9], 0x15279000
	v_lshl_add_u64 v[78:79], v[60:61], 0, s[8:9]
	global_load_dwordx2 v[114:115], v[78:79], off
	global_load_dwordx2 v[116:117], v[78:79], off offset:512
	global_load_dwordx2 v[118:119], v[78:79], off offset:1024
	global_load_dwordx2 v[120:121], v[78:79], off offset:1536
	s_mov_b64 s[8:9], 0x152f9000
	v_lshl_add_u64 v[78:79], v[60:61], 0, s[8:9]
	global_load_dwordx2 v[122:123], v[78:79], off
	global_load_dwordx2 v[124:125], v[78:79], off offset:512
	global_load_dwordx2 v[126:127], v[78:79], off offset:1024
	global_load_dwordx2 v[128:129], v[78:79], off offset:1536
	s_mov_b64 s[8:9], 0x15379000
	v_lshl_add_u64 v[78:79], v[60:61], 0, s[8:9]
	global_load_dwordx2 v[130:131], v[78:79], off
	global_load_dwordx2 v[132:133], v[78:79], off offset:512
	global_load_dwordx2 v[134:135], v[78:79], off offset:1024
	global_load_dwordx2 v[136:137], v[78:79], off offset:1536
	s_waitcnt vmcnt(11)
	v_lshlrev_b32_e32 v80, 16, v114
	v_and_b32_e32 v81, 0xffff0000, v114
	v_lshlrev_b32_e32 v82, 16, v115
	v_and_b32_e32 v83, 0xffff0000, v115
	v_pk_add_f32 v[2:3], v[2:3], v[80:81]
	v_pk_add_f32 v[74:75], v[74:75], v[82:83]
	s_waitcnt vmcnt(10)
	v_lshlrev_b32_e32 v80, 16, v116
	v_and_b32_e32 v81, 0xffff0000, v116
	v_lshlrev_b32_e32 v82, 16, v117
	v_and_b32_e32 v83, 0xffff0000, v117
	v_pk_add_f32 v[70:71], v[70:71], v[80:81]
	v_pk_add_f32 v[72:73], v[72:73], v[82:83]
	s_waitcnt vmcnt(9)
	v_lshlrev_b32_e32 v80, 16, v118
	v_and_b32_e32 v81, 0xffff0000, v118
	v_lshlrev_b32_e32 v82, 16, v119
	v_and_b32_e32 v83, 0xffff0000, v119
	v_pk_add_f32 v[66:67], v[66:67], v[80:81]
	v_pk_add_f32 v[68:69], v[68:69], v[82:83]
	s_waitcnt vmcnt(8)
	v_lshlrev_b32_e32 v80, 16, v120
	v_and_b32_e32 v81, 0xffff0000, v120
	v_lshlrev_b32_e32 v82, 16, v121
	v_and_b32_e32 v83, 0xffff0000, v121
	v_pk_add_f32 v[62:63], v[62:63], v[80:81]
	v_pk_add_f32 v[64:65], v[64:65], v[82:83]
	s_waitcnt vmcnt(7)
	v_lshlrev_b32_e32 v80, 16, v122
	v_and_b32_e32 v81, 0xffff0000, v122
	v_lshlrev_b32_e32 v82, 16, v123
	v_and_b32_e32 v83, 0xffff0000, v123
	v_pk_add_f32 v[2:3], v[2:3], v[80:81]
	v_pk_add_f32 v[74:75], v[74:75], v[82:83]
	s_waitcnt vmcnt(6)
	v_lshlrev_b32_e32 v80, 16, v124
	v_and_b32_e32 v81, 0xffff0000, v124
	v_lshlrev_b32_e32 v82, 16, v125
	v_and_b32_e32 v83, 0xffff0000, v125
	v_pk_add_f32 v[70:71], v[70:71], v[80:81]
	v_pk_add_f32 v[72:73], v[72:73], v[82:83]
	s_waitcnt vmcnt(5)
	v_lshlrev_b32_e32 v80, 16, v126
	v_and_b32_e32 v81, 0xffff0000, v126
	v_lshlrev_b32_e32 v82, 16, v127
	v_and_b32_e32 v83, 0xffff0000, v127
	v_pk_add_f32 v[66:67], v[66:67], v[80:81]
	v_pk_add_f32 v[68:69], v[68:69], v[82:83]
	s_waitcnt vmcnt(4)
	v_lshlrev_b32_e32 v80, 16, v128
	v_and_b32_e32 v81, 0xffff0000, v128
	v_lshlrev_b32_e32 v82, 16, v129
	v_and_b32_e32 v83, 0xffff0000, v129
	v_pk_add_f32 v[62:63], v[62:63], v[80:81]
	v_pk_add_f32 v[64:65], v[64:65], v[82:83]
	s_waitcnt vmcnt(3)
	v_lshlrev_b32_e32 v80, 16, v130
	v_and_b32_e32 v81, 0xffff0000, v130
	v_lshlrev_b32_e32 v82, 16, v131
	v_and_b32_e32 v83, 0xffff0000, v131
	v_pk_add_f32 v[2:3], v[2:3], v[80:81]
	v_pk_add_f32 v[74:75], v[74:75], v[82:83]
	s_waitcnt vmcnt(2)
	v_lshlrev_b32_e32 v80, 16, v132
	v_and_b32_e32 v81, 0xffff0000, v132
	v_lshlrev_b32_e32 v82, 16, v133
	v_and_b32_e32 v83, 0xffff0000, v133
	v_pk_add_f32 v[70:71], v[70:71], v[80:81]
	v_pk_add_f32 v[72:73], v[72:73], v[82:83]
	s_waitcnt vmcnt(1)
	v_lshlrev_b32_e32 v80, 16, v134
	v_and_b32_e32 v81, 0xffff0000, v134
	v_lshlrev_b32_e32 v82, 16, v135
	v_and_b32_e32 v83, 0xffff0000, v135
	v_pk_add_f32 v[66:67], v[66:67], v[80:81]
	v_pk_add_f32 v[68:69], v[68:69], v[82:83]
	s_waitcnt vmcnt(0)
	v_lshlrev_b32_e32 v80, 16, v136
	v_and_b32_e32 v81, 0xffff0000, v136
	v_lshlrev_b32_e32 v82, 16, v137
	v_and_b32_e32 v83, 0xffff0000, v137
	v_pk_add_f32 v[62:63], v[62:63], v[80:81]
	v_pk_add_f32 v[64:65], v[64:65], v[82:83]
	v_pk_mul_f32 v[78:79], v[2:3], v[2:3]
	v_pk_add_f32 v[80:81], v[2:3], v[2:3] op_sel_hi:[0,1]
	v_mul_f32_e32 v60, v3, v3
	v_mov_b32_e32 v79, v81
	v_mov_b32_e32 v61, v74
	v_pk_mul_f32 v[80:81], v[70:71], v[70:71]
	v_mul_f32_e32 v76, v74, v74
	v_pk_add_f32 v[60:61], v[60:61], v[78:79]
	v_mov_b32_e32 v77, v75
	v_add_f32_e32 v1, v70, v71
	v_pk_mul_f32 v[78:79], v[72:73], v[72:73]
	v_fmac_f32_e32 v81, v70, v70
	v_pk_mul_f32 v[84:85], v[66:67], v[66:67]
	v_pk_add_f32 v[60:61], v[76:77], v[60:61]
	v_mul_f32_e32 v172, v75, v75
	v_add_f32_e32 v77, v72, v1
	v_add_f32_e32 v78, v78, v81
	v_mul_f32_e32 v76, v73, v73
	v_add_f32_e32 v1, v66, v67
	v_pk_mul_f32 v[82:83], v[68:69], v[68:69]
	v_fmac_f32_e32 v85, v66, v66
	v_pk_mul_f32 v[94:95], v[62:63], v[62:63]
	v_mov_b32_e32 v79, v73
	v_add_f32_e32 v81, v68, v1
	v_add_f32_e32 v82, v82, v85
	v_mul_f32_e32 v80, v69, v69
	v_add_f32_e32 v1, v62, v63
	v_pk_mul_f32 v[92:93], v[64:65], v[64:65]
	v_fmac_f32_e32 v95, v62, v62
	v_pk_add_f32 v[60:61], v[60:61], v[172:173]
	v_pk_add_f32 v[76:77], v[78:79], v[76:77]
	v_mov_b32_e32 v83, v69
	v_add_f32_e32 v85, v64, v1
	v_add_f32_e32 v92, v92, v95
	v_mul_f32_e32 v84, v65, v65
	v_pk_add_f32 v[60:61], v[60:61], v[76:77]
	v_pk_add_f32 v[76:77], v[82:83], v[80:81]
	v_mov_b32_e32 v93, v65
	v_pk_add_f32 v[60:61], v[60:61], v[76:77]
	v_pk_add_f32 v[76:77], v[92:93], v[84:85]
	s_nop 0
	v_pk_add_f32 v[76:77], v[60:61], v[76:77]
